# out-projection residual epilogue de-serialised the same way (four residual loads per 16-row block together, counted vmcnt waits)
# speedup vs baseline: 1.0119x; 1.0024x over previous
; __device__ __forceinline__ unsigned cvt_pk_bf16(float lo, float hi) { unsigned r; asm volatile("v_cvt_pk_bf16_f32 %0, %1, %2" : "=v"(r) : "v"(lo), "v"(hi)); return r; }
;     __device__ __forceinline__ void operator()(const f32x4 (&acc)[2][2][4][2], const Unit& u, int wr, int wc, int fr, int fq) const {
;     ...
;         f32x4 gv[2][2];
;         if (xn) {
; #pragma unroll
;             for (int bj = 0; bj < 2; ++bj)
; #pragma unroll
;                 for (int n = 0; n < 2; ++n) gv[bj][n] = *(const f32x4*)(gain + col0 + bj * HALF + n * 16);
;         }
; #pragma unroll
;         for (int ai = 0; ai < 2; ++ai)
; #pragma unroll
;             for (int m = 0; m < 4; ++m) {
;                 const int row = row0 + ai * HALF + m * 16;
;                 const size_t off = (size_t)row * 1024 + col0;
;                 float sq = 0.f;
; #pragma unroll
;                 for (int bj = 0; bj < 2; ++bj)
; #pragma unroll
;                     for (int n = 0; n < 2; ++n) {
;                         const f32x4 b = *(const f32x4*)(base + off + bj * HALF + n * 16); const f32x4 o = b + acc[ai][bj][m][n];
;                         *(f32x4*)(out + off + bj * HALF + n * 16) = o;
;                         if (xn) { sq += (o[0] * o[0] + o[1] * o[1]) + (o[2] * o[2] + o[3] * o[3]); const f32x4 og = o * gv[bj][n];
;                             ::u32x2 w; w.x = cvt_pk_bf16(og[0], og[1]); w.y = cvt_pk_bf16(og[2], og[3]); *(::u32x2*)(xn + off + bj * HALF + n * 16) = w; }
;                     }
;                 if (xn) { sq += __shfl_xor(sq, 16); sq += __shfl_xor(sq, 32); if (fq == 0) atomicAdd(ss + row, sq); }
.LBB0_123:
	v_lshl_add_u32 v170, s43, 8, v174
	v_lshl_or_b32 v168, s42, 8, v176
	v_ashrrev_i32_e32 v171, 31, v170
	v_ashrrev_i32_e32 v169, 31, v168
	v_lshlrev_b64 v[152:153], 10, v[170:171]
	v_lshl_add_u64 v[152:153], v[152:153], 0, v[168:169]
	v_lshlrev_b64 v[182:183], 2, v[152:153]
	v_lshl_add_u64 v[64:65], v[168:169], 2, s[10:11]
	v_lshl_add_u64 v[172:173], s[8:9], 0, v[182:183]
	global_load_dwordx4 v[84:87], v[64:65], off
	global_load_dwordx4 v[80:83], v[64:65], off offset:64
	global_load_dwordx4 v[72:75], v[64:65], off offset:512
	s_nop 0
	global_load_dwordx4 v[64:67], v[64:65], off offset:576
	v_readlane_b32 s44, v249, 0
	global_load_dwordx4 v[178:181], v[172:173], off
	global_load_dwordx4 v[212:215], v[172:173], off offset:64
	global_load_dwordx4 v[216:219], v[172:173], off offset:512
	global_load_dwordx4 v[220:223], v[172:173], off offset:576
	v_readlane_b32 s46, v249, 2
	v_readlane_b32 s47, v249, 3
	v_readlane_b32 s45, v249, 1
	v_readlane_b32 s48, v249, 4
	v_readlane_b32 s49, v249, 5
	v_readlane_b32 s50, v249, 6
	v_readlane_b32 s51, v249, 7
	s_waitcnt vmcnt(3)
	v_pk_add_f32 v[180:181], v[144:145], v[180:181]
	v_pk_add_f32 v[178:179], v[142:143], v[178:179]
	v_mul_f32_e32 v145, v181, v181
	v_mul_f32_e32 v144, v179, v179
	v_lshl_add_u64 v[142:143], s[46:47], 0, v[182:183]
	v_fmac_f32_e32 v144, v178, v178
	v_fmac_f32_e32 v145, v180, v180
	global_store_dwordx4 v[142:143], v[178:181], off
	v_add_f32_e32 v182, v144, v145
	v_pk_mul_f32 v[144:145], v[86:87], v[180:181]
	v_pk_mul_f32 v[178:179], v[84:85], v[178:179]
	s_nop 0
	v_cvt_pk_bf16_f32 v178, v178, v179
	v_cvt_pk_bf16_f32 v179, v144, v145
	v_lshl_add_u64 v[144:145], v[152:153], 1, s[0:1]
	global_store_dwordx2 v[144:145], v[178:179], off
	s_waitcnt vmcnt(4)
	v_pk_add_f32 v[138:139], v[138:139], v[212:213]
	v_pk_add_f32 v[140:141], v[140:141], v[214:215]
	v_mul_f32_e32 v178, v139, v139
	global_store_dwordx4 v[142:143], v[138:141], off offset:64
	v_fmac_f32_e32 v178, v138, v138
	v_mul_f32_e32 v179, v141, v141
	v_pk_mul_f32 v[138:139], v[80:81], v[138:139]
	v_fmac_f32_e32 v179, v140, v140
	v_pk_mul_f32 v[140:141], v[82:83], v[140:141]
	v_cvt_pk_bf16_f32 v138, v138, v139
	v_add_f32_e32 v178, v178, v179
	v_cvt_pk_bf16_f32 v139, v140, v141
	global_store_dwordx2 v[144:145], v[138:139], off offset:32
	v_add_f32_e32 v178, v182, v178
	s_waitcnt vmcnt(5)
	v_pk_add_f32 v[134:135], v[134:135], v[216:217]
	v_pk_add_f32 v[136:137], v[136:137], v[218:219]
	v_mul_f32_e32 v138, v135, v135
	global_store_dwordx4 v[142:143], v[134:137], off offset:512
	v_fmac_f32_e32 v138, v134, v134
	v_mul_f32_e32 v139, v137, v137
	v_pk_mul_f32 v[134:135], v[72:73], v[134:135]
	v_fmac_f32_e32 v139, v136, v136
	v_pk_mul_f32 v[136:137], v[74:75], v[136:137]
	v_cvt_pk_bf16_f32 v134, v134, v135
	v_add_f32_e32 v138, v138, v139
	v_cvt_pk_bf16_f32 v135, v136, v137
	global_store_dwordx2 v[144:145], v[134:135], off offset:256
	v_add_f32_e32 v138, v178, v138
	s_waitcnt vmcnt(6)
	v_pk_add_f32 v[132:133], v[132:133], v[222:223]
	v_pk_add_f32 v[130:131], v[130:131], v[220:221]
	global_store_dwordx4 v[142:143], v[130:133], off offset:576
	v_pk_mul_f32 v[136:137], v[64:65], v[130:131]
	v_pk_mul_f32 v[134:135], v[66:67], v[132:133]
	v_mul_f32_e32 v131, v131, v131
	v_fmac_f32_e32 v131, v130, v130
	v_mul_f32_e32 v130, v133, v133
	v_fmac_f32_e32 v130, v132, v132
	v_and_b32_e32 v132, 64, v190
	v_add_f32_e32 v130, v131, v130
	v_xor_b32_e32 v131, 16, v190
	v_add_u32_e32 v133, 64, v132
	v_cmp_lt_i32_e32 vcc, v131, v133
	v_add_f32_e32 v130, v138, v130
	v_cvt_pk_bf16_f32 v136, v136, v137
	v_cvt_pk_bf16_f32 v137, v134, v135
	global_store_dwordx2 v[144:145], v[136:137], off offset:288
	v_cndmask_b32_e32 v131, v190, v131, vcc
	v_lshlrev_b32_e32 v132, 2, v131
	ds_bpermute_b32 v131, v132, v130
	s_waitcnt lgkmcnt(0)
	v_add_f32_e32 v134, v130, v131
	v_xor_b32_e32 v130, 32, v190
	v_cmp_lt_i32_e32 vcc, v130, v133
	s_nop 1
	v_cndmask_b32_e32 v130, v190, v130, vcc
	v_lshlrev_b32_e32 v133, 2, v130
	ds_bpermute_b32 v135, v133, v134
	v_lshl_add_u64 v[130:131], v[170:171], 2, s[4:5]
	s_and_saveexec_b64 s[22:23], s[38:39]
	s_cbranch_execz .LBB0_125
	s_waitcnt lgkmcnt(0)
	v_add_f32_e32 v134, v134, v135
	global_atomic_add_f32 v[130:131], v134, off
.LBB0_125:
	s_or_b64 exec, exec, s[22:23]
	v_or_b32_e32 v134, 16, v170
	s_waitcnt lgkmcnt(0)
	v_ashrrev_i32_e32 v135, 31, v134
	v_lshlrev_b64 v[134:135], 10, v[134:135]
	v_lshl_add_u64 v[138:139], v[134:135], 0, v[168:169]
	v_lshlrev_b64 v[140:141], 2, v[138:139]
	v_lshl_add_u64 v[142:143], s[8:9], 0, v[140:141]
	global_load_dwordx4 v[134:137], v[142:143], off
	global_load_dwordx4 v[212:215], v[142:143], off offset:64
	global_load_dwordx4 v[216:219], v[142:143], off offset:512
	global_load_dwordx4 v[220:223], v[142:143], off offset:576
	v_readlane_b32 s44, v249, 0
	v_readlane_b32 s46, v249, 2
	v_readlane_b32 s47, v249, 3
	v_lshl_add_u64 v[138:139], v[138:139], 1, s[0:1]
	v_readlane_b32 s45, v249, 1
	v_lshl_add_u64 v[140:141], s[46:47], 0, v[140:141]
	v_readlane_b32 s48, v249, 4
	v_readlane_b32 s49, v249, 5
	v_readlane_b32 s50, v249, 6
	v_readlane_b32 s51, v249, 7
	s_waitcnt vmcnt(3)
	v_pk_add_f32 v[124:125], v[124:125], v[134:135]
	v_pk_add_f32 v[126:127], v[126:127], v[136:137]
	v_pk_mul_f32 v[136:137], v[84:85], v[124:125]
	global_store_dwordx4 v[140:141], v[124:127], off
	v_pk_mul_f32 v[134:135], v[86:87], v[126:127]
	v_cvt_pk_bf16_f32 v136, v136, v137
	s_nop 0
	v_cvt_pk_bf16_f32 v137, v134, v135
	global_store_dwordx2 v[138:139], v[136:137], off
	v_mul_f32_e32 v125, v125, v125
	v_mul_f32_e32 v127, v127, v127
	v_fmac_f32_e32 v125, v124, v124
	v_fmac_f32_e32 v127, v126, v126
	v_add_f32_e32 v124, v125, v127
	s_waitcnt vmcnt(4)
; __device__ __forceinline__ unsigned cvt_pk_bf16(float lo, float hi) { unsigned r; asm volatile("v_cvt_pk_bf16_f32 %0, %1, %2" : "=v"(r) : "v"(lo), "v"(hi)); return r; }
;     __device__ __forceinline__ void operator()(const f32x4 (&acc)[2][2][4][2], const Unit& u, int wr, int wc, int fr, int fq) const {
;     ...
;                 const size_t off = (size_t)row * 1024 + col0;
;                 float sq = 0.f;
; #pragma unroll
;                 for (int bj = 0; bj < 2; ++bj)
; #pragma unroll
;                     for (int n = 0; n < 2; ++n) {
;                         const f32x4 b = *(const f32x4*)(base + off + bj * HALF + n * 16); const f32x4 o = b + acc[ai][bj][m][n];
;                         *(f32x4*)(out + off + bj * HALF + n * 16) = o;
;                         if (xn) { sq += (o[0] * o[0] + o[1] * o[1]) + (o[2] * o[2] + o[3] * o[3]); const f32x4 og = o * gv[bj][n];
;                             ::u32x2 w; w.x = cvt_pk_bf16(og[0], og[1]); w.y = cvt_pk_bf16(og[2], og[3]); *(::u32x2*)(xn + off + bj * HALF + n * 16) = w; }
;                     }
;                 if (xn) { sq += __shfl_xor(sq, 16); sq += __shfl_xor(sq, 32); if (fq == 0) atomicAdd(ss + row, sq); }
	v_pk_add_f32 v[120:121], v[120:121], v[212:213]
	v_pk_add_f32 v[122:123], v[122:123], v[214:215]
	v_pk_mul_f32 v[136:137], v[80:81], v[120:121]
	global_store_dwordx4 v[140:141], v[120:123], off offset:64
	v_pk_mul_f32 v[134:135], v[82:83], v[122:123]
	v_cvt_pk_bf16_f32 v136, v136, v137
	s_nop 0
	v_cvt_pk_bf16_f32 v137, v134, v135
	global_store_dwordx2 v[138:139], v[136:137], off offset:32
	v_mul_f32_e32 v121, v121, v121
	v_mul_f32_e32 v123, v123, v123
	v_fmac_f32_e32 v121, v120, v120
	v_fmac_f32_e32 v123, v122, v122
	v_add_f32_e32 v120, v121, v123
	v_add_f32_e32 v120, v124, v120
	s_waitcnt vmcnt(5)
	v_pk_add_f32 v[116:117], v[116:117], v[216:217]
	v_pk_add_f32 v[118:119], v[118:119], v[218:219]
	v_pk_mul_f32 v[136:137], v[72:73], v[116:117]
	global_store_dwordx4 v[140:141], v[116:119], off offset:512
	v_pk_mul_f32 v[134:135], v[74:75], v[118:119]
	v_cvt_pk_bf16_f32 v136, v136, v137
	s_nop 0
	v_cvt_pk_bf16_f32 v137, v134, v135
	global_store_dwordx2 v[138:139], v[136:137], off offset:256
	v_mul_f32_e32 v117, v117, v117
	v_mul_f32_e32 v119, v119, v119
	v_fmac_f32_e32 v117, v116, v116
	v_fmac_f32_e32 v119, v118, v118
	v_add_f32_e32 v116, v117, v119
	v_add_f32_e32 v118, v120, v116
	s_waitcnt vmcnt(6)
	v_pk_add_f32 v[116:117], v[114:115], v[222:223]
	v_pk_add_f32 v[114:115], v[112:113], v[220:221]
	v_mul_f32_e32 v113, v117, v117
	v_mul_f32_e32 v112, v115, v115
	v_fmac_f32_e32 v112, v114, v114
	v_fmac_f32_e32 v113, v116, v116
	v_add_f32_e32 v112, v112, v113
	v_add_f32_e32 v112, v118, v112
	ds_bpermute_b32 v113, v132, v112
	global_store_dwordx4 v[140:141], v[114:117], off offset:576
	s_waitcnt lgkmcnt(0)
	v_add_f32_e32 v112, v112, v113
	ds_bpermute_b32 v113, v133, v112
	v_pk_mul_f32 v[114:115], v[64:65], v[114:115]
	v_pk_mul_f32 v[116:117], v[66:67], v[116:117]
	v_cvt_pk_bf16_f32 v114, v114, v115
	s_nop 0
	v_cvt_pk_bf16_f32 v115, v116, v117
	global_store_dwordx2 v[138:139], v[114:115], off offset:288
	s_and_saveexec_b64 s[22:23], s[38:39]
	s_cbranch_execz .LBB0_127
	s_waitcnt lgkmcnt(0)
	v_add_f32_e32 v112, v112, v113
	global_atomic_add_f32 v[130:131], v112, off offset:64
.LBB0_127:
	s_or_b64 exec, exec, s[22:23]
	v_or_b32_e32 v112, 32, v170
	s_waitcnt lgkmcnt(0)
	v_ashrrev_i32_e32 v113, 31, v112
	v_lshlrev_b64 v[112:113], 10, v[112:113]
	v_lshl_add_u64 v[116:117], v[112:113], 0, v[168:169]
	v_lshlrev_b64 v[118:119], 2, v[116:117]
	v_lshl_add_u64 v[120:121], s[8:9], 0, v[118:119]
	global_load_dwordx4 v[112:115], v[120:121], off
	global_load_dwordx4 v[212:215], v[120:121], off offset:64
	global_load_dwordx4 v[216:219], v[120:121], off offset:512
	global_load_dwordx4 v[220:223], v[120:121], off offset:576
	v_readlane_b32 s44, v249, 0
	v_readlane_b32 s46, v249, 2
	v_readlane_b32 s47, v249, 3
	v_lshl_add_u64 v[116:117], v[116:117], 1, s[0:1]
	v_readlane_b32 s45, v249, 1
	v_lshl_add_u64 v[118:119], s[46:47], 0, v[118:119]
	v_readlane_b32 s48, v249, 4
	v_readlane_b32 s49, v249, 5
	v_readlane_b32 s50, v249, 6
	v_readlane_b32 s51, v249, 7
	s_waitcnt vmcnt(3)
	v_pk_add_f32 v[108:109], v[108:109], v[112:113]
	v_pk_add_f32 v[110:111], v[110:111], v[114:115]
	v_pk_mul_f32 v[114:115], v[84:85], v[108:109]
	global_store_dwordx4 v[118:119], v[108:111], off
	v_pk_mul_f32 v[112:113], v[86:87], v[110:111]
	v_cvt_pk_bf16_f32 v114, v114, v115
	s_nop 0
	v_cvt_pk_bf16_f32 v115, v112, v113
	global_store_dwordx2 v[116:117], v[114:115], off
	v_mul_f32_e32 v109, v109, v109
	v_mul_f32_e32 v111, v111, v111
	v_fmac_f32_e32 v109, v108, v108
	v_fmac_f32_e32 v111, v110, v110
	v_add_f32_e32 v108, v109, v111
	s_waitcnt vmcnt(4)
	v_pk_add_f32 v[104:105], v[104:105], v[212:213]
	v_pk_add_f32 v[106:107], v[106:107], v[214:215]
	v_pk_mul_f32 v[114:115], v[80:81], v[104:105]
	global_store_dwordx4 v[118:119], v[104:107], off offset:64
	v_pk_mul_f32 v[112:113], v[82:83], v[106:107]
	v_cvt_pk_bf16_f32 v114, v114, v115
	s_nop 0
	v_cvt_pk_bf16_f32 v115, v112, v113
	global_store_dwordx2 v[116:117], v[114:115], off offset:32
	v_mul_f32_e32 v105, v105, v105
	v_mul_f32_e32 v107, v107, v107
	v_fmac_f32_e32 v105, v104, v104
	v_fmac_f32_e32 v107, v106, v106
	v_add_f32_e32 v104, v105, v107
	v_add_f32_e32 v104, v108, v104
	s_waitcnt vmcnt(5)
	v_pk_add_f32 v[100:101], v[100:101], v[216:217]
	v_pk_add_f32 v[102:103], v[102:103], v[218:219]
	v_pk_mul_f32 v[114:115], v[72:73], v[100:101]
	global_store_dwordx4 v[118:119], v[100:103], off offset:512
	v_pk_mul_f32 v[112:113], v[74:75], v[102:103]
	v_cvt_pk_bf16_f32 v114, v114, v115
	s_nop 0
	v_cvt_pk_bf16_f32 v115, v112, v113
	global_store_dwordx2 v[116:117], v[114:115], off offset:256
	v_mul_f32_e32 v101, v101, v101
	v_mul_f32_e32 v103, v103, v103
	v_fmac_f32_e32 v101, v100, v100
	v_fmac_f32_e32 v103, v102, v102
	v_add_f32_e32 v100, v101, v103
	v_add_f32_e32 v102, v104, v100
	s_waitcnt vmcnt(6)
	v_pk_add_f32 v[100:101], v[98:99], v[222:223]
	v_pk_add_f32 v[98:99], v[96:97], v[220:221]
	v_mul_f32_e32 v97, v101, v101
	v_mul_f32_e32 v96, v99, v99
	v_fmac_f32_e32 v96, v98, v98
	v_fmac_f32_e32 v97, v100, v100
	v_add_f32_e32 v96, v96, v97
	v_add_f32_e32 v96, v102, v96
	ds_bpermute_b32 v97, v132, v96
	global_store_dwordx4 v[118:119], v[98:101], off offset:576
	s_waitcnt lgkmcnt(0)
	v_add_f32_e32 v96, v96, v97
	ds_bpermute_b32 v97, v133, v96
	v_pk_mul_f32 v[98:99], v[64:65], v[98:99]
	v_pk_mul_f32 v[100:101], v[66:67], v[100:101]
	v_cvt_pk_bf16_f32 v98, v98, v99
	s_nop 0
	v_cvt_pk_bf16_f32 v99, v100, v101
	global_store_dwordx2 v[116:117], v[98:99], off offset:288
	s_and_saveexec_b64 s[22:23], s[38:39]
	s_cbranch_execz .LBB0_129
	s_waitcnt lgkmcnt(0)
	v_add_f32_e32 v96, v96, v97
	global_atomic_add_f32 v[130:131], v96, off offset:128
; __device__ __forceinline__ unsigned cvt_pk_bf16(float lo, float hi) { unsigned r; asm volatile("v_cvt_pk_bf16_f32 %0, %1, %2" : "=v"(r) : "v"(lo), "v"(hi)); return r; }
;     __device__ __forceinline__ void operator()(const f32x4 (&acc)[2][2][4][2], const Unit& u, int wr, int wc, int fr, int fq) const {
;     ...
;                 const size_t off = (size_t)row * 1024 + col0;
;                 float sq = 0.f;
; #pragma unroll
;                 for (int bj = 0; bj < 2; ++bj)
; #pragma unroll
;                     for (int n = 0; n < 2; ++n) {
;                         const f32x4 b = *(const f32x4*)(base + off + bj * HALF + n * 16); const f32x4 o = b + acc[ai][bj][m][n];
;                         *(f32x4*)(out + off + bj * HALF + n * 16) = o;
;                         if (xn) { sq += (o[0] * o[0] + o[1] * o[1]) + (o[2] * o[2] + o[3] * o[3]); const f32x4 og = o * gv[bj][n];
;                             ::u32x2 w; w.x = cvt_pk_bf16(og[0], og[1]); w.y = cvt_pk_bf16(og[2], og[3]); *(::u32x2*)(xn + off + bj * HALF + n * 16) = w; }
;                     }
;                 if (xn) { sq += __shfl_xor(sq, 16); sq += __shfl_xor(sq, 32); if (fq == 0) atomicAdd(ss + row, sq); }
.LBB0_129:
	s_or_b64 exec, exec, s[22:23]
	v_or_b32_e32 v96, 48, v170
	s_waitcnt lgkmcnt(0)
	v_ashrrev_i32_e32 v97, 31, v96
	v_lshlrev_b64 v[96:97], 10, v[96:97]
	v_lshl_add_u64 v[100:101], v[96:97], 0, v[168:169]
	v_lshlrev_b64 v[102:103], 2, v[100:101]
	v_lshl_add_u64 v[104:105], s[8:9], 0, v[102:103]
	global_load_dwordx4 v[96:99], v[104:105], off
	global_load_dwordx4 v[212:215], v[104:105], off offset:64
	global_load_dwordx4 v[216:219], v[104:105], off offset:512
	global_load_dwordx4 v[220:223], v[104:105], off offset:576
	v_readlane_b32 s44, v249, 0
	v_readlane_b32 s46, v249, 2
	v_readlane_b32 s47, v249, 3
	v_lshl_add_u64 v[100:101], v[100:101], 1, s[0:1]
	v_readlane_b32 s45, v249, 1
	v_lshl_add_u64 v[102:103], s[46:47], 0, v[102:103]
	v_readlane_b32 s48, v249, 4
	v_readlane_b32 s49, v249, 5
	v_readlane_b32 s50, v249, 6
	v_readlane_b32 s51, v249, 7
	s_waitcnt vmcnt(3)
	v_pk_add_f32 v[92:93], v[92:93], v[96:97]
	v_pk_add_f32 v[94:95], v[94:95], v[98:99]
	v_pk_mul_f32 v[98:99], v[84:85], v[92:93]
	global_store_dwordx4 v[102:103], v[92:95], off
	v_pk_mul_f32 v[96:97], v[86:87], v[94:95]
	v_cvt_pk_bf16_f32 v98, v98, v99
	s_nop 0
	v_cvt_pk_bf16_f32 v99, v96, v97
	global_store_dwordx2 v[100:101], v[98:99], off
	v_mul_f32_e32 v93, v93, v93
	v_mul_f32_e32 v95, v95, v95
	v_fmac_f32_e32 v93, v92, v92
	v_fmac_f32_e32 v95, v94, v94
	v_add_f32_e32 v92, v93, v95
	s_waitcnt vmcnt(4)
	v_pk_add_f32 v[88:89], v[88:89], v[212:213]
	v_pk_add_f32 v[90:91], v[90:91], v[214:215]
	v_pk_mul_f32 v[98:99], v[80:81], v[88:89]
	global_store_dwordx4 v[102:103], v[88:91], off offset:64
	v_pk_mul_f32 v[96:97], v[82:83], v[90:91]
	v_cvt_pk_bf16_f32 v98, v98, v99
	s_nop 0
	v_cvt_pk_bf16_f32 v99, v96, v97
	global_store_dwordx2 v[100:101], v[98:99], off offset:32
	v_mul_f32_e32 v89, v89, v89
	v_mul_f32_e32 v91, v91, v91
	v_fmac_f32_e32 v89, v88, v88
	v_fmac_f32_e32 v91, v90, v90
	v_add_f32_e32 v88, v89, v91
	v_add_f32_e32 v88, v92, v88
	s_waitcnt vmcnt(5)
	v_pk_add_f32 v[76:77], v[76:77], v[216:217]
	v_pk_add_f32 v[78:79], v[78:79], v[218:219]
	v_pk_mul_f32 v[98:99], v[72:73], v[76:77]
	global_store_dwordx4 v[102:103], v[76:79], off offset:512
	v_pk_mul_f32 v[96:97], v[74:75], v[78:79]
	v_cvt_pk_bf16_f32 v98, v98, v99
	s_nop 0
	v_cvt_pk_bf16_f32 v99, v96, v97
	global_store_dwordx2 v[100:101], v[98:99], off offset:256
	v_mul_f32_e32 v77, v77, v77
	v_mul_f32_e32 v79, v79, v79
	v_fmac_f32_e32 v77, v76, v76
	v_fmac_f32_e32 v79, v78, v78
	v_add_f32_e32 v76, v77, v79
	v_add_f32_e32 v88, v88, v76
	s_waitcnt vmcnt(6)
	v_pk_add_f32 v[78:79], v[70:71], v[222:223]
	v_pk_add_f32 v[76:77], v[68:69], v[220:221]
	v_mul_f32_e32 v69, v79, v79
	v_mul_f32_e32 v68, v77, v77
	v_fmac_f32_e32 v68, v76, v76
	v_fmac_f32_e32 v69, v78, v78
	v_add_f32_e32 v68, v68, v69
	v_add_f32_e32 v68, v88, v68
	ds_bpermute_b32 v69, v132, v68
	global_store_dwordx4 v[102:103], v[76:79], off offset:576
	v_pk_mul_f32 v[70:71], v[66:67], v[78:79]
	s_waitcnt lgkmcnt(0)
	v_add_f32_e32 v68, v68, v69
	ds_bpermute_b32 v69, v133, v68
	v_pk_mul_f32 v[76:77], v[64:65], v[76:77]
	s_nop 0
	v_cvt_pk_bf16_f32 v76, v76, v77
	v_cvt_pk_bf16_f32 v77, v70, v71
	global_store_dwordx2 v[100:101], v[76:77], off offset:288
	s_and_saveexec_b64 s[22:23], s[38:39]
	s_cbranch_execz .LBB0_131
	s_waitcnt lgkmcnt(0)
	v_add_f32_e32 v68, v68, v69
	global_atomic_add_f32 v[130:131], v68, off offset:192
.LBB0_131:
	s_or_b64 exec, exec, s[22:23]
	s_mov_b64 s[22:23], 0x20000
	v_lshl_add_u64 v[76:77], v[152:153], 0, s[22:23]
	v_lshlrev_b64 v[78:79], 2, v[76:77]
	v_lshl_add_u64 v[88:89], s[8:9], 0, v[78:79]
	s_waitcnt lgkmcnt(0)
	global_load_dwordx4 v[68:71], v[88:89], off
	global_load_dwordx4 v[212:215], v[88:89], off offset:64
	global_load_dwordx4 v[216:219], v[88:89], off offset:512
	global_load_dwordx4 v[220:223], v[88:89], off offset:576
	v_readlane_b32 s44, v249, 0
	v_readlane_b32 s46, v249, 2
	v_readlane_b32 s47, v249, 3
	v_lshl_add_u64 v[76:77], v[76:77], 1, s[0:1]
	v_readlane_b32 s45, v249, 1
	v_lshl_add_u64 v[78:79], s[46:47], 0, v[78:79]
	v_readlane_b32 s48, v249, 4
	v_readlane_b32 s49, v249, 5
	v_readlane_b32 s50, v249, 6
	v_readlane_b32 s51, v249, 7
	s_waitcnt vmcnt(3)
	v_pk_add_f32 v[60:61], v[60:61], v[68:69]
	v_pk_add_f32 v[62:63], v[62:63], v[70:71]
	v_pk_mul_f32 v[70:71], v[84:85], v[60:61]
	global_store_dwordx4 v[78:79], v[60:63], off
	v_pk_mul_f32 v[68:69], v[86:87], v[62:63]
	v_cvt_pk_bf16_f32 v70, v70, v71
	s_nop 0
	v_cvt_pk_bf16_f32 v71, v68, v69
	global_store_dwordx2 v[76:77], v[70:71], off
	v_mul_f32_e32 v61, v61, v61
	v_mul_f32_e32 v63, v63, v63
	v_fmac_f32_e32 v61, v60, v60
	v_fmac_f32_e32 v63, v62, v62
	v_add_f32_e32 v60, v61, v63
	s_waitcnt vmcnt(4)
	v_pk_add_f32 v[56:57], v[56:57], v[212:213]
	v_pk_add_f32 v[58:59], v[58:59], v[214:215]
	v_pk_mul_f32 v[70:71], v[80:81], v[56:57]
	global_store_dwordx4 v[78:79], v[56:59], off offset:64
	v_pk_mul_f32 v[68:69], v[82:83], v[58:59]
	v_cvt_pk_bf16_f32 v70, v70, v71
	s_nop 0
	v_cvt_pk_bf16_f32 v71, v68, v69
	global_store_dwordx2 v[76:77], v[70:71], off offset:32
	v_mul_f32_e32 v57, v57, v57
	v_mul_f32_e32 v59, v59, v59
	v_fmac_f32_e32 v57, v56, v56
	v_fmac_f32_e32 v59, v58, v58
	v_add_f32_e32 v56, v57, v59
	v_add_f32_e32 v56, v60, v56
	s_waitcnt vmcnt(5)
	v_pk_add_f32 v[52:53], v[52:53], v[216:217]
	v_pk_add_f32 v[54:55], v[54:55], v[218:219]
	v_pk_mul_f32 v[70:71], v[72:73], v[52:53]
	global_store_dwordx4 v[78:79], v[52:55], off offset:512
	v_pk_mul_f32 v[68:69], v[74:75], v[54:55]
	v_cvt_pk_bf16_f32 v70, v70, v71
	s_nop 0
	v_cvt_pk_bf16_f32 v71, v68, v69
	global_store_dwordx2 v[76:77], v[70:71], off offset:256
	v_mul_f32_e32 v53, v53, v53
	v_mul_f32_e32 v55, v55, v55
	v_fmac_f32_e32 v53, v52, v52
	v_fmac_f32_e32 v55, v54, v54
	v_add_f32_e32 v52, v53, v55
	v_add_f32_e32 v54, v56, v52
	s_waitcnt vmcnt(6)
	v_pk_add_f32 v[52:53], v[50:51], v[222:223]
	v_pk_add_f32 v[50:51], v[48:49], v[220:221]
	v_mul_f32_e32 v49, v53, v53
	v_mul_f32_e32 v48, v51, v51
	v_fmac_f32_e32 v48, v50, v50
	v_fmac_f32_e32 v49, v52, v52
	v_add_f32_e32 v48, v48, v49
	v_add_f32_e32 v48, v54, v48
	ds_bpermute_b32 v49, v132, v48
	global_store_dwordx4 v[78:79], v[50:53], off offset:576
	s_waitcnt lgkmcnt(0)
	v_add_f32_e32 v48, v48, v49
	ds_bpermute_b32 v49, v133, v48
	v_pk_mul_f32 v[50:51], v[64:65], v[50:51]
	v_pk_mul_f32 v[52:53], v[66:67], v[52:53]
	v_cvt_pk_bf16_f32 v50, v50, v51
	s_nop 0
	v_cvt_pk_bf16_f32 v51, v52, v53
	global_store_dwordx2 v[76:77], v[50:51], off offset:288
	s_and_saveexec_b64 s[22:23], s[38:39]
	s_cbranch_execz .LBB0_133
	s_waitcnt lgkmcnt(0)
	v_add_f32_e32 v48, v48, v49
	global_atomic_add_f32 v[130:131], v48, off offset:512
; __device__ __forceinline__ unsigned cvt_pk_bf16(float lo, float hi) { unsigned r; asm volatile("v_cvt_pk_bf16_f32 %0, %1, %2" : "=v"(r) : "v"(lo), "v"(hi)); return r; }
;     __device__ __forceinline__ void operator()(const f32x4 (&acc)[2][2][4][2], const Unit& u, int wr, int wc, int fr, int fq) const {
;     ...
;                 const int row = row0 + ai * HALF + m * 16;
;                 const size_t off = (size_t)row * 1024 + col0;
;                 float sq = 0.f;
; #pragma unroll
;                 for (int bj = 0; bj < 2; ++bj)
; #pragma unroll
;                     for (int n = 0; n < 2; ++n) {
;                         const f32x4 b = *(const f32x4*)(base + off + bj * HALF + n * 16); const f32x4 o = b + acc[ai][bj][m][n];
;                         *(f32x4*)(out + off + bj * HALF + n * 16) = o;
;                         if (xn) { sq += (o[0] * o[0] + o[1] * o[1]) + (o[2] * o[2] + o[3] * o[3]); const f32x4 og = o * gv[bj][n];
;                             ::u32x2 w; w.x = cvt_pk_bf16(og[0], og[1]); w.y = cvt_pk_bf16(og[2], og[3]); *(::u32x2*)(xn + off + bj * HALF + n * 16) = w; }
;                     }
;                 if (xn) { sq += __shfl_xor(sq, 16); sq += __shfl_xor(sq, 32); if (fq == 0) atomicAdd(ss + row, sq); }
.LBB0_133:
	s_or_b64 exec, exec, s[22:23]
	s_mov_b64 s[22:23], 0x24000
	v_lshl_add_u64 v[52:53], v[152:153], 0, s[22:23]
	v_lshlrev_b64 v[54:55], 2, v[52:53]
	v_lshl_add_u64 v[56:57], s[8:9], 0, v[54:55]
	s_waitcnt lgkmcnt(0)
	global_load_dwordx4 v[48:51], v[56:57], off
	global_load_dwordx4 v[212:215], v[56:57], off offset:64
	global_load_dwordx4 v[216:219], v[56:57], off offset:512
	global_load_dwordx4 v[220:223], v[56:57], off offset:576
	v_readlane_b32 s44, v249, 0
	v_readlane_b32 s46, v249, 2
	v_readlane_b32 s47, v249, 3
	v_lshl_add_u64 v[52:53], v[52:53], 1, s[0:1]
	v_readlane_b32 s45, v249, 1
	v_lshl_add_u64 v[54:55], s[46:47], 0, v[54:55]
	v_readlane_b32 s48, v249, 4
	v_readlane_b32 s49, v249, 5
	v_readlane_b32 s50, v249, 6
	v_readlane_b32 s51, v249, 7
	s_waitcnt vmcnt(3)
	v_pk_add_f32 v[44:45], v[44:45], v[48:49]
	v_pk_add_f32 v[46:47], v[46:47], v[50:51]
	v_pk_mul_f32 v[50:51], v[84:85], v[44:45]
	global_store_dwordx4 v[54:55], v[44:47], off
	v_pk_mul_f32 v[48:49], v[86:87], v[46:47]
	v_cvt_pk_bf16_f32 v50, v50, v51
	s_nop 0
	v_cvt_pk_bf16_f32 v51, v48, v49
	global_store_dwordx2 v[52:53], v[50:51], off
	v_mul_f32_e32 v45, v45, v45
	v_mul_f32_e32 v47, v47, v47
	v_fmac_f32_e32 v45, v44, v44
	v_fmac_f32_e32 v47, v46, v46
	v_add_f32_e32 v44, v45, v47
	s_waitcnt vmcnt(4)
	v_pk_add_f32 v[40:41], v[40:41], v[212:213]
	v_pk_add_f32 v[42:43], v[42:43], v[214:215]
	v_pk_mul_f32 v[50:51], v[80:81], v[40:41]
	global_store_dwordx4 v[54:55], v[40:43], off offset:64
	v_pk_mul_f32 v[48:49], v[82:83], v[42:43]
	v_cvt_pk_bf16_f32 v50, v50, v51
	s_nop 0
	v_cvt_pk_bf16_f32 v51, v48, v49
	global_store_dwordx2 v[52:53], v[50:51], off offset:32
	v_mul_f32_e32 v41, v41, v41
	v_mul_f32_e32 v43, v43, v43
	v_fmac_f32_e32 v41, v40, v40
	v_fmac_f32_e32 v43, v42, v42
	v_add_f32_e32 v40, v41, v43
	v_add_f32_e32 v40, v44, v40
	s_waitcnt vmcnt(5)
	v_pk_add_f32 v[36:37], v[36:37], v[216:217]
	v_pk_add_f32 v[38:39], v[38:39], v[218:219]
	v_pk_mul_f32 v[50:51], v[72:73], v[36:37]
	global_store_dwordx4 v[54:55], v[36:39], off offset:512
	v_pk_mul_f32 v[48:49], v[74:75], v[38:39]
	v_cvt_pk_bf16_f32 v50, v50, v51
	s_nop 0
	v_cvt_pk_bf16_f32 v51, v48, v49
	global_store_dwordx2 v[52:53], v[50:51], off offset:256
	v_mul_f32_e32 v37, v37, v37
	v_mul_f32_e32 v39, v39, v39
	v_fmac_f32_e32 v37, v36, v36
	v_fmac_f32_e32 v39, v38, v38
	v_add_f32_e32 v36, v37, v39
	v_add_f32_e32 v38, v40, v36
	s_waitcnt vmcnt(6)
	v_pk_add_f32 v[36:37], v[34:35], v[222:223]
	v_pk_add_f32 v[34:35], v[32:33], v[220:221]
	v_mul_f32_e32 v33, v37, v37
	v_mul_f32_e32 v32, v35, v35
	v_fmac_f32_e32 v32, v34, v34
	v_fmac_f32_e32 v33, v36, v36
	v_add_f32_e32 v32, v32, v33
	v_add_f32_e32 v32, v38, v32
	ds_bpermute_b32 v33, v132, v32
	global_store_dwordx4 v[54:55], v[34:37], off offset:576
	s_waitcnt lgkmcnt(0)
	v_add_f32_e32 v32, v32, v33
	ds_bpermute_b32 v33, v133, v32
	v_pk_mul_f32 v[34:35], v[64:65], v[34:35]
	v_pk_mul_f32 v[36:37], v[66:67], v[36:37]
	v_cvt_pk_bf16_f32 v34, v34, v35
	s_nop 0
	v_cvt_pk_bf16_f32 v35, v36, v37
	global_store_dwordx2 v[52:53], v[34:35], off offset:288
	s_and_saveexec_b64 s[22:23], s[38:39]
	s_cbranch_execz .LBB0_135
	s_waitcnt lgkmcnt(0)
	v_add_f32_e32 v32, v32, v33
	global_atomic_add_f32 v[130:131], v32, off offset:576
; __device__ __forceinline__ unsigned cvt_pk_bf16(float lo, float hi) { unsigned r; asm volatile("v_cvt_pk_bf16_f32 %0, %1, %2" : "=v"(r) : "v"(lo), "v"(hi)); return r; }
;     __device__ __forceinline__ void operator()(const f32x4 (&acc)[2][2][4][2], const Unit& u, int wr, int wc, int fr, int fq) const {
;     ...
;                 const int row = row0 + ai * HALF + m * 16;
;                 const size_t off = (size_t)row * 1024 + col0;
;                 float sq = 0.f;
; #pragma unroll
;                 for (int bj = 0; bj < 2; ++bj)
; #pragma unroll
;                     for (int n = 0; n < 2; ++n) {
;                         const f32x4 b = *(const f32x4*)(base + off + bj * HALF + n * 16); const f32x4 o = b + acc[ai][bj][m][n];
;                         *(f32x4*)(out + off + bj * HALF + n * 16) = o;
;                         if (xn) { sq += (o[0] * o[0] + o[1] * o[1]) + (o[2] * o[2] + o[3] * o[3]); const f32x4 og = o * gv[bj][n];
;                             ::u32x2 w; w.x = cvt_pk_bf16(og[0], og[1]); w.y = cvt_pk_bf16(og[2], og[3]); *(::u32x2*)(xn + off + bj * HALF + n * 16) = w; }
;                     }
;                 if (xn) { sq += __shfl_xor(sq, 16); sq += __shfl_xor(sq, 32); if (fq == 0) atomicAdd(ss + row, sq); }
.LBB0_135:
	s_or_b64 exec, exec, s[22:23]
	s_mov_b64 s[22:23], 0x28000
	v_lshl_add_u64 v[36:37], v[152:153], 0, s[22:23]
	v_lshlrev_b64 v[38:39], 2, v[36:37]
	v_lshl_add_u64 v[40:41], s[8:9], 0, v[38:39]
	s_waitcnt lgkmcnt(0)
	global_load_dwordx4 v[32:35], v[40:41], off
	global_load_dwordx4 v[212:215], v[40:41], off offset:64
	global_load_dwordx4 v[216:219], v[40:41], off offset:512
	global_load_dwordx4 v[220:223], v[40:41], off offset:576
	v_readlane_b32 s44, v249, 0
	v_readlane_b32 s46, v249, 2
	v_readlane_b32 s47, v249, 3
	v_lshl_add_u64 v[36:37], v[36:37], 1, s[0:1]
	v_readlane_b32 s45, v249, 1
	v_lshl_add_u64 v[38:39], s[46:47], 0, v[38:39]
	v_readlane_b32 s48, v249, 4
	v_readlane_b32 s49, v249, 5
	v_readlane_b32 s50, v249, 6
	v_readlane_b32 s51, v249, 7
	s_waitcnt vmcnt(3)
	v_pk_add_f32 v[28:29], v[28:29], v[32:33]
	v_pk_add_f32 v[30:31], v[30:31], v[34:35]
	v_pk_mul_f32 v[34:35], v[84:85], v[28:29]
	global_store_dwordx4 v[38:39], v[28:31], off
	v_pk_mul_f32 v[32:33], v[86:87], v[30:31]
	v_cvt_pk_bf16_f32 v34, v34, v35
	s_nop 0
	v_cvt_pk_bf16_f32 v35, v32, v33
	global_store_dwordx2 v[36:37], v[34:35], off
	v_mul_f32_e32 v29, v29, v29
	v_mul_f32_e32 v31, v31, v31
	v_fmac_f32_e32 v29, v28, v28
	v_fmac_f32_e32 v31, v30, v30
	v_add_f32_e32 v28, v29, v31
	s_waitcnt vmcnt(4)
	v_pk_add_f32 v[24:25], v[24:25], v[212:213]
	v_pk_add_f32 v[26:27], v[26:27], v[214:215]
	v_pk_mul_f32 v[34:35], v[80:81], v[24:25]
	global_store_dwordx4 v[38:39], v[24:27], off offset:64
	v_pk_mul_f32 v[32:33], v[82:83], v[26:27]
	v_cvt_pk_bf16_f32 v34, v34, v35
	s_nop 0
	v_cvt_pk_bf16_f32 v35, v32, v33
	global_store_dwordx2 v[36:37], v[34:35], off offset:32
	v_mul_f32_e32 v25, v25, v25
	v_mul_f32_e32 v27, v27, v27
	v_fmac_f32_e32 v25, v24, v24
	v_fmac_f32_e32 v27, v26, v26
	v_add_f32_e32 v24, v25, v27
	v_add_f32_e32 v24, v28, v24
	s_waitcnt vmcnt(5)
	v_pk_add_f32 v[20:21], v[20:21], v[216:217]
	v_pk_add_f32 v[22:23], v[22:23], v[218:219]
	v_pk_mul_f32 v[34:35], v[72:73], v[20:21]
	global_store_dwordx4 v[38:39], v[20:23], off offset:512
	v_pk_mul_f32 v[32:33], v[74:75], v[22:23]
	v_cvt_pk_bf16_f32 v34, v34, v35
	s_nop 0
	v_cvt_pk_bf16_f32 v35, v32, v33
	global_store_dwordx2 v[36:37], v[34:35], off offset:256
	v_mul_f32_e32 v21, v21, v21
	v_mul_f32_e32 v23, v23, v23
	v_fmac_f32_e32 v21, v20, v20
	v_fmac_f32_e32 v23, v22, v22
	v_add_f32_e32 v20, v21, v23
	v_add_f32_e32 v22, v24, v20
	s_waitcnt vmcnt(6)
	v_pk_add_f32 v[20:21], v[18:19], v[222:223]
	v_pk_add_f32 v[18:19], v[16:17], v[220:221]
	v_mul_f32_e32 v17, v21, v21
	v_mul_f32_e32 v16, v19, v19
	v_fmac_f32_e32 v16, v18, v18
	v_fmac_f32_e32 v17, v20, v20
	v_add_f32_e32 v16, v16, v17
	v_add_f32_e32 v16, v22, v16
	ds_bpermute_b32 v17, v132, v16
	global_store_dwordx4 v[38:39], v[18:21], off offset:576
	s_waitcnt lgkmcnt(0)
	v_add_f32_e32 v16, v16, v17
	ds_bpermute_b32 v17, v133, v16
	v_pk_mul_f32 v[18:19], v[64:65], v[18:19]
	v_pk_mul_f32 v[20:21], v[66:67], v[20:21]
	v_cvt_pk_bf16_f32 v18, v18, v19
	s_nop 0
	v_cvt_pk_bf16_f32 v19, v20, v21
	global_store_dwordx2 v[36:37], v[18:19], off offset:288
	s_and_saveexec_b64 s[22:23], s[38:39]
	s_cbranch_execz .LBB0_137
	s_waitcnt lgkmcnt(0)
	v_add_f32_e32 v16, v16, v17
	global_atomic_add_f32 v[130:131], v16, off offset:640
.LBB0_137:
	s_or_b64 exec, exec, s[22:23]
	s_mov_b64 s[22:23], 0x2c000
	v_lshl_add_u64 v[20:21], v[152:153], 0, s[22:23]
	v_lshlrev_b64 v[22:23], 2, v[20:21]
	v_lshl_add_u64 v[24:25], s[8:9], 0, v[22:23]
	s_waitcnt lgkmcnt(0)
	global_load_dwordx4 v[16:19], v[24:25], off
	global_load_dwordx4 v[212:215], v[24:25], off offset:64
	global_load_dwordx4 v[216:219], v[24:25], off offset:512
	global_load_dwordx4 v[220:223], v[24:25], off offset:576
	v_readlane_b32 s44, v249, 0
	v_readlane_b32 s46, v249, 2
	v_readlane_b32 s47, v249, 3
	v_lshl_add_u64 v[20:21], v[20:21], 1, s[0:1]
	v_readlane_b32 s45, v249, 1
	v_lshl_add_u64 v[22:23], s[46:47], 0, v[22:23]
	v_readlane_b32 s48, v249, 4
	v_readlane_b32 s49, v249, 5
	v_readlane_b32 s50, v249, 6
	v_readlane_b32 s51, v249, 7
	s_waitcnt vmcnt(3)
	v_pk_add_f32 v[12:13], v[12:13], v[16:17]
	v_pk_add_f32 v[14:15], v[14:15], v[18:19]
	v_pk_mul_f32 v[18:19], v[84:85], v[12:13]
	global_store_dwordx4 v[22:23], v[12:15], off
	v_pk_mul_f32 v[16:17], v[86:87], v[14:15]
	v_cvt_pk_bf16_f32 v18, v18, v19
	s_nop 0
	v_cvt_pk_bf16_f32 v19, v16, v17
	global_store_dwordx2 v[20:21], v[18:19], off
	v_mul_f32_e32 v13, v13, v13
	v_mul_f32_e32 v15, v15, v15
	v_fmac_f32_e32 v13, v12, v12
	v_fmac_f32_e32 v15, v14, v14
	v_add_f32_e32 v12, v13, v15
	s_waitcnt vmcnt(4)
	v_pk_add_f32 v[8:9], v[8:9], v[212:213]
	v_pk_add_f32 v[10:11], v[10:11], v[214:215]
	v_pk_mul_f32 v[18:19], v[80:81], v[8:9]
	global_store_dwordx4 v[22:23], v[8:11], off offset:64
	v_pk_mul_f32 v[16:17], v[82:83], v[10:11]
	v_cvt_pk_bf16_f32 v18, v18, v19
	s_nop 0
	v_cvt_pk_bf16_f32 v19, v16, v17
	global_store_dwordx2 v[20:21], v[18:19], off offset:32
	v_mul_f32_e32 v9, v9, v9
	v_mul_f32_e32 v11, v11, v11
	v_fmac_f32_e32 v9, v8, v8
	v_fmac_f32_e32 v11, v10, v10
	v_add_f32_e32 v8, v9, v11
	v_add_f32_e32 v8, v12, v8
	s_waitcnt vmcnt(5)
	v_pk_add_f32 v[4:5], v[4:5], v[216:217]
	v_pk_add_f32 v[6:7], v[6:7], v[218:219]
	v_pk_mul_f32 v[18:19], v[72:73], v[4:5]
	global_store_dwordx4 v[22:23], v[4:7], off offset:512
	v_pk_mul_f32 v[16:17], v[74:75], v[6:7]
	v_cvt_pk_bf16_f32 v18, v18, v19
	s_nop 0
	v_cvt_pk_bf16_f32 v19, v16, v17
	global_store_dwordx2 v[20:21], v[18:19], off offset:256
	v_mul_f32_e32 v5, v5, v5
	v_mul_f32_e32 v7, v7, v7
	v_fmac_f32_e32 v5, v4, v4
	v_fmac_f32_e32 v7, v6, v6
	v_add_f32_e32 v4, v5, v7
	v_add_f32_e32 v6, v8, v4
	s_waitcnt vmcnt(6)
	v_pk_add_f32 v[4:5], v[2:3], v[222:223]
	v_pk_add_f32 v[2:3], v[0:1], v[220:221]
	v_mul_f32_e32 v1, v5, v5
	v_mul_f32_e32 v0, v3, v3
	v_fmac_f32_e32 v0, v2, v2
	v_fmac_f32_e32 v1, v4, v4
	v_add_f32_e32 v0, v0, v1
	v_add_f32_e32 v0, v6, v0
	ds_bpermute_b32 v1, v132, v0
	global_store_dwordx4 v[22:23], v[2:5], off offset:576
	s_waitcnt lgkmcnt(0)
	v_add_f32_e32 v0, v0, v1
	ds_bpermute_b32 v1, v133, v0
	v_pk_mul_f32 v[2:3], v[64:65], v[2:3]
	v_pk_mul_f32 v[4:5], v[66:67], v[4:5]
	v_cvt_pk_bf16_f32 v2, v2, v3
	s_nop 0
	v_cvt_pk_bf16_f32 v3, v4, v5
	global_store_dwordx2 v[20:21], v[2:3], off offset:288
	s_and_saveexec_b64 s[22:23], s[38:39]
	s_cbranch_execz .LBB0_139
	s_waitcnt lgkmcnt(0)
	v_add_f32_e32 v0, v0, v1
	global_atomic_add_f32 v[130:131], v0, off offset:704
